# P2 WY solve: block right-hand-side init de-serialised (all LDS reads of a 16-row block in flight, one wait) instead of 16 serial read-wait-multiply groups
# speedup vs baseline: 1.0286x; 1.0094x over previous
.LBB0_376:
	s_lshl_b32 s33, s11, 4
	s_mul_i32 s13, s11, 0x1100
	s_lshl_b32 s10, s33, 2
	s_add_i32 s15, s10, 0x21400
	v_mov_b32_e32 v18, s15
	ds_read_b128 v[20:23], v18
	ds_read_b128 v[24:27], v18 offset:16
	ds_read_b128 v[28:31], v18 offset:32
	ds_read_b128 v[32:35], v18 offset:48
	s_mov_b64 s[6:7], exec
	s_and_b64 exec, s[6:7], s[46:47]
	s_cbranch_execz .Lri_u
	v_add_u32_e32 v19, s13, v133
	ds_read_u16 v0, v19
	ds_read_u16 v1, v19 offset:272
	ds_read_u16 v2, v19 offset:544
	ds_read_u16 v3, v19 offset:816
	ds_read_u16 v4, v19 offset:1088
	ds_read_u16 v5, v19 offset:1360
	ds_read_u16 v6, v19 offset:1632
	ds_read_u16 v7, v19 offset:1904
	ds_read_u16 v8, v19 offset:2176
	ds_read_u16 v9, v19 offset:2448
	ds_read_u16 v10, v19 offset:2720
	ds_read_u16 v11, v19 offset:2992
	ds_read_u16 v12, v19 offset:3264
	ds_read_u16 v13, v19 offset:3536
	ds_read_u16 v14, v19 offset:3808
	ds_read_u16 v15, v19 offset:4080
	s_add_i32 s15, s10, 0x21600
	v_mov_b32_e32 v17, s15
	ds_read_b128 v[240:243], v17
	ds_read_b128 v[244:247], v17 offset:16
	ds_read_b128 v[248:251], v17 offset:32
	ds_read_b128 v[252:255], v17 offset:48
	s_waitcnt lgkmcnt(0)
	v_lshlrev_b32_e32 v0, 16, v0
	v_mul_f32_e32 v0, v20, v0
	v_mul_f32_e32 v0, v240, v0
	v_lshlrev_b32_e32 v1, 16, v1
	v_mul_f32_e32 v1, v21, v1
	v_mul_f32_e32 v1, v241, v1
	v_lshlrev_b32_e32 v2, 16, v2
	v_mul_f32_e32 v2, v22, v2
	v_mul_f32_e32 v2, v242, v2
	v_lshlrev_b32_e32 v3, 16, v3
	v_mul_f32_e32 v3, v23, v3
	v_mul_f32_e32 v3, v243, v3
	v_lshlrev_b32_e32 v4, 16, v4
	v_mul_f32_e32 v4, v24, v4
	v_mul_f32_e32 v4, v244, v4
	v_lshlrev_b32_e32 v5, 16, v5
	v_mul_f32_e32 v5, v25, v5
	v_mul_f32_e32 v5, v245, v5
	v_lshlrev_b32_e32 v6, 16, v6
	v_mul_f32_e32 v6, v26, v6
	v_mul_f32_e32 v6, v246, v6
	v_lshlrev_b32_e32 v7, 16, v7
	v_mul_f32_e32 v7, v27, v7
	v_mul_f32_e32 v7, v247, v7
	v_lshlrev_b32_e32 v8, 16, v8
	v_mul_f32_e32 v8, v28, v8
	v_mul_f32_e32 v8, v248, v8
	v_lshlrev_b32_e32 v9, 16, v9
	v_mul_f32_e32 v9, v29, v9
	v_mul_f32_e32 v9, v249, v9
	v_lshlrev_b32_e32 v10, 16, v10
	v_mul_f32_e32 v10, v30, v10
	v_mul_f32_e32 v10, v250, v10
	v_lshlrev_b32_e32 v11, 16, v11
	v_mul_f32_e32 v11, v31, v11
	v_mul_f32_e32 v11, v251, v11
	v_lshlrev_b32_e32 v12, 16, v12
	v_mul_f32_e32 v12, v32, v12
	v_mul_f32_e32 v12, v252, v12
	v_lshlrev_b32_e32 v13, 16, v13
	v_mul_f32_e32 v13, v33, v13
	v_mul_f32_e32 v13, v253, v13
	v_lshlrev_b32_e32 v14, 16, v14
	v_mul_f32_e32 v14, v34, v14
	v_mul_f32_e32 v14, v254, v14
	v_lshlrev_b32_e32 v15, 16, v15
	v_mul_f32_e32 v15, v35, v15
	v_mul_f32_e32 v15, v255, v15
.Lri_u:
	s_andn2_b64 exec, s[6:7], s[46:47]
	s_cbranch_execz .Lri_done
	s_mul_i32 s10, s11, 0x2100
	v_add_u32_e32 v19, s10, v132
	ds_read_b32 v0, v19
	ds_read_b32 v1, v19 offset:528
	ds_read_b32 v2, v19 offset:1056
	ds_read_b32 v3, v19 offset:1584
	ds_read_b32 v4, v19 offset:2112
	ds_read_b32 v5, v19 offset:2640
	ds_read_b32 v6, v19 offset:3168
	ds_read_b32 v7, v19 offset:3696
	ds_read_b32 v8, v19 offset:4224
	ds_read_b32 v9, v19 offset:4752
	ds_read_b32 v10, v19 offset:5280
	ds_read_b32 v11, v19 offset:5808
	ds_read_b32 v12, v19 offset:6336
	ds_read_b32 v13, v19 offset:6864
	ds_read_b32 v14, v19 offset:7392
	ds_read_b32 v15, v19 offset:7920
	s_waitcnt lgkmcnt(0)
	v_mul_f32_e32 v0, v0, v20
	v_mul_f32_e32 v1, v1, v21
	v_mul_f32_e32 v2, v2, v22
	v_mul_f32_e32 v3, v3, v23
	v_mul_f32_e32 v4, v4, v24
	v_mul_f32_e32 v5, v5, v25
	v_mul_f32_e32 v6, v6, v26
	v_mul_f32_e32 v7, v7, v27
	v_mul_f32_e32 v8, v8, v28
	v_mul_f32_e32 v9, v9, v29
	v_mul_f32_e32 v10, v10, v30
	v_mul_f32_e32 v11, v11, v31
	v_mul_f32_e32 v12, v12, v32
	v_mul_f32_e32 v13, v13, v33
	v_mul_f32_e32 v14, v14, v34
	v_mul_f32_e32 v15, v15, v35
.Lri_done:
	s_mov_b64 exec, s[6:7]
	s_mul_i32 s10, s11, 0x2100
	v_add_u32_e32 v16, s10, v132
	s_or_b32 s10, s33, 1
	s_mul_i32 s50, s10, 0x110
	s_mul_i32 s15, s10, 0x210
	v_add_u32_e32 v17, s15, v132
	s_cmp_eq_u32 s11, 0
	s_cbranch_scc1 .LBB0_375
